# E65: E64 plus lazy causal-mask position (v195 computed from s16 only in the diagonal-tile mask block; one VALU fewer per prompt-FoX tile)
# baseline (speedup 1.0000x reference)
.LBB0_1387:
	s_or_b64 exec, exec, s[18:19]
	s_movk_i32 s15, 0x90
	v_mul_lo_u32 v147, v4, s15
	v_lshlrev_b32_e32 v153, 4, v8
	v_add3_u32 v8, 0, v147, v153
	s_waitcnt lgkmcnt(0)
	s_barrier
	s_barrier
	ds_write_b128 v8, v[130:133]
	v_mad_u64_u32 v[8:9], s[16:17], v4, 48, v[8:9]
	v_mul_lo_u32 v174, v6, s15
	v_lshlrev_b32_e32 v175, 4, v5
	ds_write_b128 v8, v[134:137] offset:18432
	v_add3_u32 v8, 0, v174, v175
	v_lshrrev_b32_e32 v2, 2, v2
	s_cmp_lt_i32 s13, s12
	s_movk_i32 s18, 0xc0
	ds_write_b128 v8, v[138:141]
	v_mad_u64_u32 v[8:9], s[16:17], v6, 48, v[8:9]
	v_and_or_b32 v5, v2, 3, v216
	v_and_or_b32 v2, v2, 4, v225
	v_mov_b32_e32 v16, v3
	v_mov_b32_e32 v17, v3
	s_cselect_b64 s[84:85], -1, 0
	s_add_i32 s14, s9, 0x7f
	s_add_i32 s13, s13, s8
	v_mul_lo_u32 v173, v4, s18
	v_mul_lo_u32 v191, v6, s18
	ds_write_b128 v8, v[142:145] offset:18432
	v_lshlrev_b32_e32 v193, 3, v2
	v_mul_u32_u24_e32 v194, 0xc0, v5
	v_add_u32_e32 v196, 0x80, v6
	v_add_u32_e32 v197, 0x80, v4
	v_mov_b32_e32 v2, v3
	v_mov_b32_e32 v4, v3
	v_mov_b32_e32 v5, v3
	v_mov_b32_e32 v6, v3
	v_mov_b32_e32 v7, v3
	v_mov_b32_e32 v8, v3
	v_mov_b32_e32 v9, v3
	v_mov_b32_e32 v10, v3
	v_mov_b32_e32 v11, v3
	v_mov_b32_e32 v12, v3
	v_mov_b32_e32 v13, v3
	v_mov_b32_e32 v14, v3
	v_mov_b32_e32 v15, v3
	v_mov_b64_e32 v[32:33], v[16:17]
	v_mov_b64_e32 v[48:49], v[16:17]
	s_lshr_b32 s14, s14, 7
	s_movk_i32 s72, 0x90
	s_movk_i32 s73, 0xc0
	s_add_i32 s15, s13, 31
	v_add_u32_e32 v205, s13, v188
	s_mov_b32 s16, 0
	v_mov_b32_e32 v158, 0xf149f2ca
	v_mov_b32_e32 v204, 0xf149f2ca
	v_mov_b32_e32 v192, 0
	v_mov_b32_e32 v198, v187
	v_mov_b64_e32 v[30:31], v[14:15]
	v_mov_b64_e32 v[28:29], v[12:13]
	v_mov_b64_e32 v[26:27], v[10:11]
	v_mov_b64_e32 v[24:25], v[8:9]
	v_mov_b64_e32 v[22:23], v[6:7]
	v_mov_b64_e32 v[20:21], v[4:5]
	v_mov_b64_e32 v[18:19], v[2:3]
	v_mov_b64_e32 v[46:47], v[14:15]
	v_mov_b64_e32 v[44:45], v[12:13]
	v_mov_b64_e32 v[42:43], v[10:11]
	v_mov_b64_e32 v[40:41], v[8:9]
	v_mov_b64_e32 v[38:39], v[6:7]
	v_mov_b64_e32 v[36:37], v[4:5]
	v_mov_b64_e32 v[34:35], v[2:3]
	s_mov_b32 s18, 0
	s_waitcnt lgkmcnt(0)
	s_barrier
	v_mov_b32_e32 v4, v197
	v_ashrrev_i32_e32 v5, 31, v4
	v_lshlrev_b64 v[4:5], 9, v[4:5]
	v_lshl_add_u64 v[4:5], v[4:5], 0, v[148:149]
	v_lshlrev_b64 v[4:5], 1, v[4:5]
	v_lshl_add_u64 v[248:249], s[64:65], 0, v[4:5]
	v_lshl_add_u64 v[246:247], s[66:67], 0, v[4:5]
	v_mov_b32_e32 v4, v196
	v_ashrrev_i32_e32 v5, 31, v4
	v_lshlrev_b64 v[4:5], 9, v[4:5]
	v_lshl_add_u64 v[4:5], v[4:5], 0, v[156:157]
	v_lshlrev_b64 v[4:5], 1, v[4:5]
	v_lshl_add_u64 v[250:251], s[64:65], 0, v[4:5]
	v_lshl_add_u64 v[252:253], s[66:67], 0, v[4:5]
	s_mov_b32 s100, 0x20000
	s_mov_b32 s101, 0
	v_add_u32_e32 v200, v147, v153
	v_add_u32_e32 v201, v191, v175
	v_add_u32_e32 v202, v174, v175
	v_add_u32_e32 v203, v173, v153

.LBB0_1390:
	s_cmp_le_i32 s16, s15
	s_cselect_b64 s[20:21], -1, 0
	s_and_b64 s[20:21], s[84:85], s[20:21]
	s_andn2_b64 vcc, exec, s[20:21]
	s_cbranch_vccnz .LBB0_1396
	s_bitcmp1_b32 s18, 0
	s_cselect_b32 s18, 0xa800, 0
	s_add_i32 s70, s18, 0
	ds_read_b128 v[82:85], v198
	ds_read_b128 v[86:89], v198 offset:32
	ds_read_b128 v[90:93], v198 offset:64
	ds_read_b128 v[94:97], v198 offset:96
	v_add3_u32 v2, s70, v214, v186
	ds_read_b128 v[226:229], v2
	ds_read_b128 v[230:233], v2 offset:32
	ds_read_b128 v[234:237], v2 offset:64
	ds_read_b128 v[238:241], v2 offset:96
	ds_read_b128 v[50:53], v198 offset:128
	ds_read_b128 v[54:57], v198 offset:160
	ds_read_b128 v[58:61], v198 offset:192
	ds_read_b128 v[62:65], v198 offset:224
	s_add_i32 s18, s16, 0x7f
	s_cmp_le_i32 s18, s13
	s_waitcnt lgkmcnt(4)
	v_mfma_f32_32x32x16_bf16 v[82:97], v[226:229], v[114:117], v[82:97]
	ds_read_b128 v[4:7], v2 offset:4608
	v_mfma_f32_32x32x16_bf16 v[82:97], v[230:233], v[118:121], v[82:97]
	ds_read_b128 v[8:11], v2 offset:4640
	v_mfma_f32_32x32x16_bf16 v[82:97], v[234:237], v[122:125], v[82:97]
	ds_read_b128 v[12:15], v2 offset:4672
	v_mfma_f32_32x32x16_bf16 v[82:97], v[238:241], v[126:129], v[82:97]
	ds_read_b128 v[160:163], v2 offset:4704
	ds_read_b128 v[66:69], v198 offset:256
	ds_read_b128 v[70:73], v198 offset:288
	ds_read_b128 v[74:77], v198 offset:320
	ds_read_b128 v[78:81], v198 offset:352
	s_waitcnt lgkmcnt(4)
	v_mfma_f32_32x32x16_bf16 v[50:65], v[4:7], v[114:117], v[50:65]
	ds_read_b128 v[226:229], v2 offset:9216
	v_mfma_f32_32x32x16_bf16 v[50:65], v[8:11], v[118:121], v[50:65]
	ds_read_b128 v[230:233], v2 offset:9248
	v_mfma_f32_32x32x16_bf16 v[50:65], v[12:15], v[122:125], v[50:65]
	ds_read_b128 v[234:237], v2 offset:9280
	v_mfma_f32_32x32x16_bf16 v[50:65], v[160:163], v[126:129], v[50:65]
	ds_read_b128 v[238:241], v2 offset:9312
	ds_read_b128 v[98:101], v198 offset:384
	ds_read_b128 v[102:105], v198 offset:416
	ds_read_b128 v[106:109], v198 offset:448
	ds_read_b128 v[110:113], v198 offset:480
	s_waitcnt lgkmcnt(4)
	v_mfma_f32_32x32x16_bf16 v[66:81], v[226:229], v[114:117], v[66:81]
	ds_read_b128 v[4:7], v2 offset:13824
	v_mfma_f32_32x32x16_bf16 v[66:81], v[230:233], v[118:121], v[66:81]
	ds_read_b128 v[8:11], v2 offset:13856
	v_mfma_f32_32x32x16_bf16 v[66:81], v[234:237], v[122:125], v[66:81]
	ds_read_b128 v[12:15], v2 offset:13888
	v_mfma_f32_32x32x16_bf16 v[66:81], v[238:241], v[126:129], v[66:81]
	ds_read_b128 v[160:163], v2 offset:13920
	s_waitcnt lgkmcnt(3)
	v_mfma_f32_32x32x16_bf16 v[98:113], v[4:7], v[114:117], v[98:113]
	s_waitcnt lgkmcnt(2)
	v_mfma_f32_32x32x16_bf16 v[98:113], v[8:11], v[118:121], v[98:113]
	s_waitcnt lgkmcnt(1)
	v_mfma_f32_32x32x16_bf16 v[98:113], v[12:15], v[122:125], v[98:113]
	s_waitcnt lgkmcnt(0)
	v_mfma_f32_32x32x16_bf16 v[98:113], v[160:163], v[126:129], v[98:113]
	s_cbranch_scc1 .LBB0_1393
	v_subrev_u32_e32 v195, s16, v205
	v_cmp_gt_i32_e64 s[46:47], 26, v195
	v_cmp_gt_i32_e64 s[48:49], 27, v195
	v_cmp_gt_i32_e64 s[44:45], 25, v195
	s_and_b64 s[46:47], s[48:49], s[46:47]
	v_cmp_gt_i32_e64 s[42:43], 24, v195
	v_cndmask_b32_e64 v97, v97, v190, s[48:49]
	v_cndmask_b32_e64 v96, v96, v190, s[46:47]
	s_and_b64 s[44:45], s[46:47], s[44:45]
	v_cmp_gt_i32_e64 s[46:47], 58, v195
	v_cmp_gt_i32_e64 s[48:49], 59, v195
	v_cmp_gt_i32_e64 s[40:41], 19, v195
	v_cndmask_b32_e64 v95, v95, v190, s[44:45]
	s_and_b64 s[42:43], s[44:45], s[42:43]
	v_cmp_gt_i32_e64 s[44:45], 57, v195
	s_and_b64 s[46:47], s[48:49], s[46:47]
	v_cmp_gt_i32_e64 s[38:39], 18, v195
	v_cndmask_b32_e64 v94, v94, v190, s[42:43]
	s_and_b64 s[40:41], s[42:43], s[40:41]
	v_cmp_gt_i32_e64 s[42:43], 56, v195
	v_cndmask_b32_e64 v65, v65, v190, s[48:49]
	v_cndmask_b32_e64 v64, v64, v190, s[46:47]
	s_and_b64 s[44:45], s[46:47], s[44:45]
	s_movk_i32 s46, 0x5a
	s_movk_i32 s48, 0x5b
	v_cmp_gt_i32_e64 s[36:37], 17, v195
	v_cndmask_b32_e64 v93, v93, v190, s[40:41]
	s_and_b64 s[38:39], s[40:41], s[38:39]
	v_cmp_gt_i32_e64 s[40:41], 51, v195
	v_cndmask_b32_e64 v63, v63, v190, s[44:45]
	s_and_b64 s[42:43], s[44:45], s[42:43]
	s_movk_i32 s44, 0x59
	v_cmp_gt_i32_e64 s[46:47], s46, v195
	v_cmp_gt_i32_e64 s[48:49], s48, v195
	v_cmp_gt_i32_e64 s[34:35], 16, v195
	v_cndmask_b32_e64 v92, v92, v190, s[38:39]
	s_and_b64 s[36:37], s[38:39], s[36:37]
	v_cmp_gt_i32_e64 s[38:39], 50, v195
	v_cndmask_b32_e64 v62, v62, v190, s[42:43]
	s_and_b64 s[40:41], s[42:43], s[40:41]
	s_movk_i32 s42, 0x58
	v_cmp_gt_i32_e64 s[44:45], s44, v195
	s_and_b64 s[46:47], s[48:49], s[46:47]
	v_cmp_gt_i32_e64 s[30:31], 11, v195
	v_cndmask_b32_e64 v91, v91, v190, s[36:37]
	s_and_b64 s[34:35], s[36:37], s[34:35]
	v_cmp_gt_i32_e64 s[36:37], 49, v195
	v_cndmask_b32_e64 v61, v61, v190, s[40:41]
	s_and_b64 s[38:39], s[40:41], s[38:39]
	s_movk_i32 s40, 0x53
	v_cmp_gt_i32_e64 s[42:43], s42, v195
	s_and_b64 s[44:45], s[46:47], s[44:45]
	v_cmp_gt_i32_e64 s[28:29], 10, v195
	v_cndmask_b32_e64 v90, v90, v190, s[34:35]
	s_and_b64 s[30:31], s[34:35], s[30:31]
	v_cmp_gt_i32_e64 s[34:35], 48, v195
	v_cndmask_b32_e64 v60, v60, v190, s[38:39]
	s_and_b64 s[36:37], s[38:39], s[36:37]
	s_movk_i32 s38, 0x52
	v_cmp_gt_i32_e64 s[40:41], s40, v195
	v_cndmask_b32_e64 v81, v81, v190, s[48:49]
	v_cndmask_b32_e64 v80, v80, v190, s[46:47]
	s_and_b64 s[42:43], s[44:45], s[42:43]
	s_movk_i32 s46, 0x7a
	s_movk_i32 s48, 0x7b
	v_cmp_gt_i32_e64 s[26:27], 9, v195
	v_cndmask_b32_e64 v89, v89, v190, s[30:31]
	s_and_b64 s[28:29], s[30:31], s[28:29]
	v_cmp_gt_i32_e64 s[30:31], 43, v195
	v_cndmask_b32_e64 v59, v59, v190, s[36:37]
	s_and_b64 s[34:35], s[36:37], s[34:35]
	s_movk_i32 s36, 0x51
	v_cmp_gt_i32_e64 s[38:39], s38, v195
	v_cndmask_b32_e64 v79, v79, v190, s[44:45]
	s_and_b64 s[40:41], s[42:43], s[40:41]
	s_movk_i32 s44, 0x79
	v_cmp_gt_i32_e64 s[46:47], s46, v195
	v_cmp_gt_i32_e64 s[48:49], s48, v195
	v_cmp_gt_i32_e64 s[24:25], 8, v195
	v_cndmask_b32_e64 v88, v88, v190, s[28:29]
	s_and_b64 s[26:27], s[28:29], s[26:27]
	v_cmp_gt_i32_e64 s[28:29], 42, v195
	v_cndmask_b32_e64 v58, v58, v190, s[34:35]
	s_and_b64 s[30:31], s[34:35], s[30:31]
	s_movk_i32 s34, 0x50
	v_cmp_gt_i32_e64 s[36:37], s36, v195
	v_cndmask_b32_e64 v78, v78, v190, s[42:43]
	s_and_b64 s[38:39], s[40:41], s[38:39]
	s_movk_i32 s42, 0x78
	v_cmp_gt_i32_e64 s[44:45], s44, v195
	s_and_b64 s[46:47], s[48:49], s[46:47]
	v_cmp_gt_i32_e64 s[22:23], 3, v195
	v_cndmask_b32_e64 v87, v87, v190, s[26:27]
	s_and_b64 s[24:25], s[26:27], s[24:25]
	v_cmp_gt_i32_e64 s[26:27], 41, v195
	v_cndmask_b32_e64 v57, v57, v190, s[30:31]
	s_and_b64 s[28:29], s[30:31], s[28:29]
	s_movk_i32 s30, 0x4b
	v_cmp_gt_i32_e64 s[34:35], s34, v195
	v_cndmask_b32_e64 v77, v77, v190, s[40:41]
	s_and_b64 s[36:37], s[38:39], s[36:37]
	s_movk_i32 s40, 0x73
	v_cmp_gt_i32_e64 s[42:43], s42, v195
	s_and_b64 s[44:45], s[46:47], s[44:45]
	v_cmp_gt_i32_e64 s[20:21], 2, v195
	v_cndmask_b32_e64 v86, v86, v190, s[24:25]
	s_and_b64 s[22:23], s[24:25], s[22:23]
	v_cmp_gt_i32_e64 s[24:25], 40, v195
	v_cndmask_b32_e64 v56, v56, v190, s[28:29]
	s_and_b64 s[26:27], s[28:29], s[26:27]
	s_movk_i32 s28, 0x4a
	v_cmp_gt_i32_e64 s[30:31], s30, v195
	v_cndmask_b32_e64 v76, v76, v190, s[38:39]
	s_and_b64 s[34:35], s[36:37], s[34:35]
	s_movk_i32 s38, 0x72
	v_cmp_gt_i32_e64 s[40:41], s40, v195
	s_and_b64 s[42:43], s[44:45], s[42:43]
	v_cmp_gt_i32_e64 s[18:19], 1, v195
	v_cndmask_b32_e64 v85, v85, v190, s[22:23]
	s_and_b64 s[20:21], s[22:23], s[20:21]
	v_cmp_gt_i32_e64 s[22:23], 35, v195
	v_cndmask_b32_e64 v55, v55, v190, s[26:27]
	s_and_b64 s[24:25], s[26:27], s[24:25]
	s_movk_i32 s26, 0x49
	v_cmp_gt_i32_e64 s[28:29], s28, v195
	v_cndmask_b32_e64 v75, v75, v190, s[36:37]
	s_and_b64 s[30:31], s[34:35], s[30:31]
	s_movk_i32 s36, 0x71
	v_cmp_gt_i32_e64 s[38:39], s38, v195
	s_and_b64 s[40:41], s[42:43], s[40:41]
	v_cmp_gt_i32_e32 vcc, 0, v195
	v_cndmask_b32_e64 v84, v84, v190, s[20:21]
	s_and_b64 s[18:19], s[20:21], s[18:19]
	v_cmp_gt_i32_e64 s[20:21], 34, v195
	v_cndmask_b32_e64 v54, v54, v190, s[24:25]
	s_and_b64 s[22:23], s[24:25], s[22:23]
	s_movk_i32 s24, 0x48
	v_cmp_gt_i32_e64 s[26:27], s26, v195
	v_cndmask_b32_e64 v74, v74, v190, s[34:35]
	s_and_b64 s[28:29], s[30:31], s[28:29]
	s_movk_i32 s34, 0x70
	v_cmp_gt_i32_e64 s[36:37], s36, v195
	s_and_b64 s[38:39], s[40:41], s[38:39]
	v_cndmask_b32_e64 v83, v83, v190, s[18:19]
	s_and_b64 vcc, s[18:19], vcc
	v_cmp_gt_i32_e64 s[18:19], 33, v195
	v_cndmask_b32_e64 v53, v53, v190, s[22:23]
	s_and_b64 s[20:21], s[22:23], s[20:21]
	s_movk_i32 s22, 0x43
	v_cmp_gt_i32_e64 s[24:25], s24, v195
	v_cndmask_b32_e64 v73, v73, v190, s[30:31]
	s_and_b64 s[26:27], s[28:29], s[26:27]
	s_movk_i32 s30, 0x6b
	v_cmp_gt_i32_e64 s[34:35], s34, v195
	s_and_b64 s[36:37], s[38:39], s[36:37]
	v_cndmask_b32_e32 v82, v82, v190, vcc
	v_cmp_gt_i32_e32 vcc, 32, v195
	v_cndmask_b32_e64 v52, v52, v190, s[20:21]
	s_and_b64 s[18:19], s[20:21], s[18:19]
	s_movk_i32 s20, 0x42
	v_cmp_gt_i32_e64 s[22:23], s22, v195
	v_cndmask_b32_e64 v72, v72, v190, s[28:29]
	s_and_b64 s[24:25], s[26:27], s[24:25]
	s_movk_i32 s28, 0x6a
	v_cmp_gt_i32_e64 s[30:31], s30, v195
	s_and_b64 s[34:35], s[36:37], s[34:35]
	v_cndmask_b32_e64 v51, v51, v190, s[18:19]
	s_and_b64 vcc, s[18:19], vcc
	s_movk_i32 s18, 0x41
	v_cmp_gt_i32_e64 s[20:21], s20, v195
	v_cndmask_b32_e64 v71, v71, v190, s[26:27]
	s_and_b64 s[22:23], s[24:25], s[22:23]
	s_movk_i32 s26, 0x69
	v_cmp_gt_i32_e64 s[28:29], s28, v195
	s_and_b64 s[30:31], s[34:35], s[30:31]
	v_cmp_gt_i32_e64 s[18:19], s18, v195
	v_cndmask_b32_e64 v70, v70, v190, s[24:25]
	s_and_b64 s[20:21], s[22:23], s[20:21]
	s_movk_i32 s24, 0x68
	v_cmp_gt_i32_e64 s[26:27], s26, v195
	s_and_b64 s[28:29], s[30:31], s[28:29]
	v_cndmask_b32_e32 v50, v50, v190, vcc
	v_cmp_gt_i32_e32 vcc, 64, v195
	v_cndmask_b32_e64 v69, v69, v190, s[22:23]
	s_and_b64 s[18:19], s[20:21], s[18:19]
	s_movk_i32 s22, 0x63
	v_cmp_gt_i32_e64 s[24:25], s24, v195
	s_and_b64 s[26:27], s[28:29], s[26:27]
	v_cndmask_b32_e64 v68, v68, v190, s[20:21]
	v_cndmask_b32_e64 v67, v67, v190, s[18:19]
	s_and_b64 vcc, s[18:19], vcc
	s_movk_i32 s18, 0x60
	s_movk_i32 s20, 0x62
	v_cmp_gt_i32_e64 s[22:23], s22, v195
	s_and_b64 s[24:25], s[26:27], s[24:25]
	v_cndmask_b32_e32 v66, v66, v190, vcc
	v_cmp_gt_i32_e32 vcc, s18, v195
	s_movk_i32 s18, 0x61
	v_cmp_gt_i32_e64 s[20:21], s20, v195
	s_and_b64 s[22:23], s[24:25], s[22:23]
	v_cmp_gt_i32_e64 s[18:19], s18, v195
	s_and_b64 s[20:21], s[22:23], s[20:21]
	s_and_b64 s[18:19], s[20:21], s[18:19]
	s_and_b64 vcc, s[18:19], vcc
	v_cndmask_b32_e64 v113, v113, v190, s[48:49]
	v_cndmask_b32_e64 v112, v112, v190, s[46:47]
	v_cndmask_b32_e64 v111, v111, v190, s[44:45]
	v_cndmask_b32_e64 v110, v110, v190, s[42:43]
	v_cndmask_b32_e64 v109, v109, v190, s[40:41]
	v_cndmask_b32_e64 v108, v108, v190, s[38:39]
	v_cndmask_b32_e64 v107, v107, v190, s[36:37]
	v_cndmask_b32_e64 v106, v106, v190, s[34:35]
	v_cndmask_b32_e64 v105, v105, v190, s[30:31]
	v_cndmask_b32_e64 v104, v104, v190, s[28:29]
	v_cndmask_b32_e64 v103, v103, v190, s[26:27]
	v_cndmask_b32_e64 v102, v102, v190, s[24:25]
	v_cndmask_b32_e64 v101, v101, v190, s[22:23]
	v_cndmask_b32_e64 v100, v100, v190, s[20:21]
	v_cndmask_b32_e64 v99, v99, v190, s[18:19]
	v_cndmask_b32_e32 v98, v98, v190, vcc

.LBB0_1398:
	s_addk_i32 s16, 0x80
	v_add_u32_e32 v198, 0x200, v198
	s_cmp_eq_u32 s14, s17
	s_waitcnt lgkmcnt(0)
	s_barrier
	s_cbranch_scc1 .LBB0_1400
	s_mov_b32 s18, s17
	s_branch .LBB0_1388
